# T12: attention cross-half max/sum exchange in registers (v_permlane32_swap) instead of ds_bpermute + lgkmcnt(0); V fragment reads issued before the exp block (diff), diff + DSA
# speedup vs baseline: 1.0006x; 1.0006x over previous
; #define LAS __attribute__((address_space(3)))
; __device__ __forceinline__ f32x16 mma32(const h16x8 a, const h16x8 b, const f32x16 c) { return __builtin_amdgcn_mfma_f32_32x32x16_f16(a, b, c, 0, 0, 0); }
; __device__ __forceinline__ void dsa_attn_item(CParams& p, LAS unsigned char* lds, int b, int qb, int tid_in, int wave) {
;     ...
;                 const unsigned mw = (unsigned)(mk >> (32 * sub));
;                 if (__ballot(mw != 0u) == 0ull) continue;
;                 f32x16 sc;
; #pragma unroll
;                 for (int i = 0; i < 16; ++i) sc[i] = 0.f;
; #pragma unroll
;                 for (int s = 0; s < 8; ++s) sc = mma32(*(const LAS h16x8*)(Ks + (32 * sub + r) * 136 + 16 * s + 8 * hh), qf[s], sc);
;                 float mx = -INFINITY;
; #pragma unroll
;                 for (int i = 0; i < 16; ++i) { const int ko = (i & 3) + 8 * (i >> 2) + 4 * hh; const int dist = qp - (k0 + 32 * sub + ko);
;                     float bias = bfar; if (!far) bias = bdh[dist < 0 ? 0 : (dist < 128 ? dist : 128)];
;                     const float v = ((mw >> ko) & 1u) ? sc[i] + bias : -INFINITY; sc[i] = v; mx = fmaxf(mx, v); }
;                 mx = fmaxf(mx, __shfl_xor(mx, 32));
;                 const float m_new = fmaxf(m_run, mx);
;                 const float msafe = (m_new == -INFINITY) ? 0.f : m_new;
;                 const float alpha = __builtin_amdgcn_exp2f(m_run - msafe);
;                 const bool resc = __ballot(m_new > m_run) != 0ull;
;                 float ls = 0.f;
; #pragma unroll
;                 for (int i = 0; i < 16; ++i) { const float e = __builtin_amdgcn_exp2f(sc[i] - msafe); sc[i] = e; ls += e; }
;                 ls += __shfl_xor(ls, 32);
;                 l_run = l_run * alpha + ls; m_run = m_new;
;                 if (resc) {
; #pragma unroll
;                     for (int d = 0; d < 4; ++d)
; #pragma unroll
;                         for (int i = 0; i < 16; ++i) o[d][i] *= alpha;
;                 }
.LdsaA_s0_msk:
	v_bfe_i32 v80, v214, 0, 1
	v_bfi_b32 v236, v80, v236, v225
	v_bfe_i32 v81, v214, 1, 1
	v_bfi_b32 v237, v81, v237, v225
	v_bfe_i32 v82, v214, 2, 1
	v_bfi_b32 v238, v82, v238, v225
	v_bfe_i32 v83, v214, 3, 1
	v_bfi_b32 v239, v83, v239, v225
	v_bfe_i32 v80, v214, 8, 1
	v_bfi_b32 v240, v80, v240, v225
	v_bfe_i32 v81, v214, 9, 1
	v_bfi_b32 v241, v81, v241, v225
	v_bfe_i32 v82, v214, 10, 1
	v_bfi_b32 v242, v82, v242, v225
	v_bfe_i32 v83, v214, 11, 1
	v_bfi_b32 v243, v83, v243, v225
	v_bfe_i32 v80, v214, 16, 1
	v_bfi_b32 v244, v80, v244, v225
	v_bfe_i32 v81, v214, 17, 1
	v_bfi_b32 v245, v81, v245, v225
	v_bfe_i32 v82, v214, 18, 1
	v_bfi_b32 v246, v82, v246, v225
	v_bfe_i32 v83, v214, 19, 1
	v_bfi_b32 v247, v83, v247, v225
	v_bfe_i32 v80, v214, 24, 1
	v_bfi_b32 v248, v80, v248, v225
	v_bfe_i32 v81, v214, 25, 1
	v_bfi_b32 v249, v81, v249, v225
	v_bfe_i32 v82, v214, 26, 1
	v_bfi_b32 v250, v82, v250, v225
	v_bfe_i32 v83, v214, 27, 1
	v_bfi_b32 v251, v83, v251, v225
	v_max3_f32 v84, v236, v237, v238
	v_max3_f32 v84, v84, v239, v240
	v_max3_f32 v84, v84, v241, v242
	v_max3_f32 v84, v84, v243, v244
	v_max3_f32 v84, v84, v245, v246
	v_max3_f32 v84, v84, v247, v248
	v_max3_f32 v84, v84, v249, v250
	v_max_f32_e32 v84, v84, v251
	s_waitcnt lgkmcnt(0)
	v_add_f32_e32 v84, v84, v200
	v_mov_b32_e32 v215, v84
	s_nop 1
	v_permlane32_swap_b32 v215, v84
	v_max3_f32 v85, v201, v84, v215
	v_cmp_neq_f32_e32 vcc, s78, v85
	s_nop 1
	v_cndmask_b32_e32 v86, 0, v85, vcc
	v_sub_f32_e32 v88, v201, v86
	v_exp_f32_e32 v88, v88
	v_cmp_gt_f32_e32 vcc, v85, v201
	v_sub_f32_e32 v90, v86, v200
	v_mov_b32_e32 v201, v85
	v_pk_add_f32 v[236:237], v[236:237], v[90:91] op_sel_hi:[1,0] neg_lo:[0,1] neg_hi:[0,1]
	v_pk_add_f32 v[238:239], v[238:239], v[90:91] op_sel_hi:[1,0] neg_lo:[0,1] neg_hi:[0,1]
	v_pk_add_f32 v[240:241], v[240:241], v[90:91] op_sel_hi:[1,0] neg_lo:[0,1] neg_hi:[0,1]
	v_pk_add_f32 v[242:243], v[242:243], v[90:91] op_sel_hi:[1,0] neg_lo:[0,1] neg_hi:[0,1]
	v_pk_add_f32 v[244:245], v[244:245], v[90:91] op_sel_hi:[1,0] neg_lo:[0,1] neg_hi:[0,1]
	v_pk_add_f32 v[246:247], v[246:247], v[90:91] op_sel_hi:[1,0] neg_lo:[0,1] neg_hi:[0,1]
	v_pk_add_f32 v[248:249], v[248:249], v[90:91] op_sel_hi:[1,0] neg_lo:[0,1] neg_hi:[0,1]
	v_pk_add_f32 v[250:251], v[250:251], v[90:91] op_sel_hi:[1,0] neg_lo:[0,1] neg_hi:[0,1]
	v_exp_f32_e32 v236, v236
	v_exp_f32_e32 v237, v237
	v_exp_f32_e32 v238, v238
	v_exp_f32_e32 v239, v239
	v_exp_f32_e32 v240, v240
	v_exp_f32_e32 v241, v241
	v_exp_f32_e32 v242, v242
	v_exp_f32_e32 v243, v243
	v_exp_f32_e32 v244, v244
	v_exp_f32_e32 v245, v245
	v_exp_f32_e32 v246, v246
	v_exp_f32_e32 v247, v247
	v_exp_f32_e32 v248, v248
	v_exp_f32_e32 v249, v249
	v_exp_f32_e32 v250, v250
	v_exp_f32_e32 v251, v251
	v_pk_add_f32 v[92:93], v[236:237], v[238:239]
	v_pk_add_f32 v[92:93], v[92:93], v[240:241]
	v_pk_add_f32 v[92:93], v[92:93], v[242:243]
	v_pk_add_f32 v[92:93], v[92:93], v[244:245]
	v_pk_add_f32 v[92:93], v[92:93], v[246:247]
	v_pk_add_f32 v[92:93], v[92:93], v[248:249]
	v_pk_add_f32 v[92:93], v[92:93], v[250:251]
	s_nop 0
	v_add_f32_e32 v92, v92, v93
	v_mov_b32_e32 v215, v92
	v_cvt_pk_f16_f32 v232, v236, v237
	v_cvt_pk_f16_f32 v233, v238, v239
	v_cvt_pk_f16_f32 v234, v240, v241
	v_cvt_pk_f16_f32 v235, v242, v243
	v_cvt_pk_f16_f32 v228, v244, v245
	v_cvt_pk_f16_f32 v229, v246, v247
	v_cvt_pk_f16_f32 v230, v248, v249
	v_cvt_pk_f16_f32 v231, v250, v251
	v_permlane32_swap_b32 v215, v92
	v_add_f32_e32 v92, v92, v215
	v_fma_f32 v198, v198, v88, v92
	ds_read_b128 v[236:239], v199 offset:34848
	ds_read_b128 v[240:243], v199 offset:39424
	ds_read_b128 v[244:247], v199 offset:44128
	ds_read_b128 v[248:251], v199 offset:48704
	s_cbranch_vccz .LdsaA_s0_noresc
	v_pk_mul_f32 v[64:65], v[64:65], v[88:89] op_sel_hi:[1,0]
	v_pk_mul_f32 v[66:67], v[66:67], v[88:89] op_sel_hi:[1,0]
	v_pk_mul_f32 v[68:69], v[68:69], v[88:89] op_sel_hi:[1,0]
	v_pk_mul_f32 v[70:71], v[70:71], v[88:89] op_sel_hi:[1,0]
	v_pk_mul_f32 v[72:73], v[72:73], v[88:89] op_sel_hi:[1,0]
	v_pk_mul_f32 v[74:75], v[74:75], v[88:89] op_sel_hi:[1,0]
	v_pk_mul_f32 v[76:77], v[76:77], v[88:89] op_sel_hi:[1,0]
	v_pk_mul_f32 v[78:79], v[78:79], v[88:89] op_sel_hi:[1,0]
	v_pk_mul_f32 v[48:49], v[48:49], v[88:89] op_sel_hi:[1,0]
	v_pk_mul_f32 v[50:51], v[50:51], v[88:89] op_sel_hi:[1,0]
	v_pk_mul_f32 v[52:53], v[52:53], v[88:89] op_sel_hi:[1,0]
	v_pk_mul_f32 v[54:55], v[54:55], v[88:89] op_sel_hi:[1,0]
	v_pk_mul_f32 v[56:57], v[56:57], v[88:89] op_sel_hi:[1,0]
	v_pk_mul_f32 v[58:59], v[58:59], v[88:89] op_sel_hi:[1,0]
	v_pk_mul_f32 v[60:61], v[60:61], v[88:89] op_sel_hi:[1,0]
	v_pk_mul_f32 v[62:63], v[62:63], v[88:89] op_sel_hi:[1,0]
	v_pk_mul_f32 v[32:33], v[32:33], v[88:89] op_sel_hi:[1,0]
	v_pk_mul_f32 v[34:35], v[34:35], v[88:89] op_sel_hi:[1,0]
	v_pk_mul_f32 v[36:37], v[36:37], v[88:89] op_sel_hi:[1,0]
	v_pk_mul_f32 v[38:39], v[38:39], v[88:89] op_sel_hi:[1,0]
	v_pk_mul_f32 v[40:41], v[40:41], v[88:89] op_sel_hi:[1,0]
	v_pk_mul_f32 v[42:43], v[42:43], v[88:89] op_sel_hi:[1,0]
	v_pk_mul_f32 v[44:45], v[44:45], v[88:89] op_sel_hi:[1,0]
	v_pk_mul_f32 v[46:47], v[46:47], v[88:89] op_sel_hi:[1,0]
	v_pk_mul_f32 v[16:17], v[16:17], v[88:89] op_sel_hi:[1,0]
	v_pk_mul_f32 v[18:19], v[18:19], v[88:89] op_sel_hi:[1,0]
	v_pk_mul_f32 v[20:21], v[20:21], v[88:89] op_sel_hi:[1,0]
	v_pk_mul_f32 v[22:23], v[22:23], v[88:89] op_sel_hi:[1,0]
	v_pk_mul_f32 v[24:25], v[24:25], v[88:89] op_sel_hi:[1,0]
	v_pk_mul_f32 v[26:27], v[26:27], v[88:89] op_sel_hi:[1,0]
	v_pk_mul_f32 v[28:29], v[28:29], v[88:89] op_sel_hi:[1,0]
	v_pk_mul_f32 v[30:31], v[30:31], v[88:89] op_sel_hi:[1,0]

; #define LAS __attribute__((address_space(3)))
; __device__ __forceinline__ f32x16 mma32(const h16x8 a, const h16x8 b, const f32x16 c) { return __builtin_amdgcn_mfma_f32_32x32x16_f16(a, b, c, 0, 0, 0); }
; __device__ __forceinline__ void dsa_attn_item(CParams& p, LAS unsigned char* lds, int b, int qb, int tid_in, int wave) {
;     ...
;                 const unsigned mw = (unsigned)(mk >> (32 * sub));
;                 if (__ballot(mw != 0u) == 0ull) continue;
;                 f32x16 sc;
; #pragma unroll
;                 for (int i = 0; i < 16; ++i) sc[i] = 0.f;
; #pragma unroll
;                 for (int s = 0; s < 8; ++s) sc = mma32(*(const LAS h16x8*)(Ks + (32 * sub + r) * 136 + 16 * s + 8 * hh), qf[s], sc);
;                 float mx = -INFINITY;
; #pragma unroll
;                 for (int i = 0; i < 16; ++i) { const int ko = (i & 3) + 8 * (i >> 2) + 4 * hh; const int dist = qp - (k0 + 32 * sub + ko);
;                     float bias = bfar; if (!far) bias = bdh[dist < 0 ? 0 : (dist < 128 ? dist : 128)];
;                     const float v = ((mw >> ko) & 1u) ? sc[i] + bias : -INFINITY; sc[i] = v; mx = fmaxf(mx, v); }
;                 mx = fmaxf(mx, __shfl_xor(mx, 32));
;                 const float m_new = fmaxf(m_run, mx);
;                 const float msafe = (m_new == -INFINITY) ? 0.f : m_new;
;                 const float alpha = __builtin_amdgcn_exp2f(m_run - msafe);
;                 const bool resc = __ballot(m_new > m_run) != 0ull;
;                 float ls = 0.f;
; #pragma unroll
;                 for (int i = 0; i < 16; ++i) { const float e = __builtin_amdgcn_exp2f(sc[i] - msafe); sc[i] = e; ls += e; }
;                 ls += __shfl_xor(ls, 32);
;                 l_run = l_run * alpha + ls; m_run = m_new;
;                 if (resc) {
; #pragma unroll
;                     for (int d = 0; d < 4; ++d)
; #pragma unroll
;                         for (int i = 0; i < 16; ++i) o[d][i] *= alpha;
;                 }
.LdsaA_s1_msk:
	v_bfe_i32 v80, v214, 0, 1
	v_bfi_b32 v236, v80, v236, v225
	v_bfe_i32 v81, v214, 1, 1
	v_bfi_b32 v237, v81, v237, v225
	v_bfe_i32 v82, v214, 2, 1
	v_bfi_b32 v238, v82, v238, v225
	v_bfe_i32 v83, v214, 3, 1
	v_bfi_b32 v239, v83, v239, v225
	v_bfe_i32 v80, v214, 8, 1
	v_bfi_b32 v240, v80, v240, v225
	v_bfe_i32 v81, v214, 9, 1
	v_bfi_b32 v241, v81, v241, v225
	v_bfe_i32 v82, v214, 10, 1
	v_bfi_b32 v242, v82, v242, v225
	v_bfe_i32 v83, v214, 11, 1
	v_bfi_b32 v243, v83, v243, v225
	v_bfe_i32 v80, v214, 16, 1
	v_bfi_b32 v244, v80, v244, v225
	v_bfe_i32 v81, v214, 17, 1
	v_bfi_b32 v245, v81, v245, v225
	v_bfe_i32 v82, v214, 18, 1
	v_bfi_b32 v246, v82, v246, v225
	v_bfe_i32 v83, v214, 19, 1
	v_bfi_b32 v247, v83, v247, v225
	v_bfe_i32 v80, v214, 24, 1
	v_bfi_b32 v248, v80, v248, v225
	v_bfe_i32 v81, v214, 25, 1
	v_bfi_b32 v249, v81, v249, v225
	v_bfe_i32 v82, v214, 26, 1
	v_bfi_b32 v250, v82, v250, v225
	v_bfe_i32 v83, v214, 27, 1
	v_bfi_b32 v251, v83, v251, v225
	v_max3_f32 v84, v236, v237, v238
	v_max3_f32 v84, v84, v239, v240
	v_max3_f32 v84, v84, v241, v242
	v_max3_f32 v84, v84, v243, v244
	v_max3_f32 v84, v84, v245, v246
	v_max3_f32 v84, v84, v247, v248
	v_max3_f32 v84, v84, v249, v250
	v_max_f32_e32 v84, v84, v251
	s_waitcnt lgkmcnt(0)
	v_add_f32_e32 v84, v84, v200
	v_mov_b32_e32 v215, v84
	s_nop 1
	v_permlane32_swap_b32 v215, v84
	v_max3_f32 v85, v201, v84, v215
	v_cmp_neq_f32_e32 vcc, s78, v85
	s_nop 1
	v_cndmask_b32_e32 v86, 0, v85, vcc
	v_sub_f32_e32 v88, v201, v86
	v_exp_f32_e32 v88, v88
	v_cmp_gt_f32_e32 vcc, v85, v201
	v_sub_f32_e32 v90, v86, v200
	v_mov_b32_e32 v201, v85
	v_pk_add_f32 v[236:237], v[236:237], v[90:91] op_sel_hi:[1,0] neg_lo:[0,1] neg_hi:[0,1]
	v_pk_add_f32 v[238:239], v[238:239], v[90:91] op_sel_hi:[1,0] neg_lo:[0,1] neg_hi:[0,1]
	v_pk_add_f32 v[240:241], v[240:241], v[90:91] op_sel_hi:[1,0] neg_lo:[0,1] neg_hi:[0,1]
	v_pk_add_f32 v[242:243], v[242:243], v[90:91] op_sel_hi:[1,0] neg_lo:[0,1] neg_hi:[0,1]
	v_pk_add_f32 v[244:245], v[244:245], v[90:91] op_sel_hi:[1,0] neg_lo:[0,1] neg_hi:[0,1]
	v_pk_add_f32 v[246:247], v[246:247], v[90:91] op_sel_hi:[1,0] neg_lo:[0,1] neg_hi:[0,1]
	v_pk_add_f32 v[248:249], v[248:249], v[90:91] op_sel_hi:[1,0] neg_lo:[0,1] neg_hi:[0,1]
	v_pk_add_f32 v[250:251], v[250:251], v[90:91] op_sel_hi:[1,0] neg_lo:[0,1] neg_hi:[0,1]
	v_exp_f32_e32 v236, v236
	v_exp_f32_e32 v237, v237
	v_exp_f32_e32 v238, v238
	v_exp_f32_e32 v239, v239
	v_exp_f32_e32 v240, v240
	v_exp_f32_e32 v241, v241
	v_exp_f32_e32 v242, v242
	v_exp_f32_e32 v243, v243
	v_exp_f32_e32 v244, v244
	v_exp_f32_e32 v245, v245
	v_exp_f32_e32 v246, v246
	v_exp_f32_e32 v247, v247
	v_exp_f32_e32 v248, v248
	v_exp_f32_e32 v249, v249
	v_exp_f32_e32 v250, v250
	v_exp_f32_e32 v251, v251
	v_pk_add_f32 v[92:93], v[236:237], v[238:239]
	v_pk_add_f32 v[92:93], v[92:93], v[240:241]
	v_pk_add_f32 v[92:93], v[92:93], v[242:243]
	v_pk_add_f32 v[92:93], v[92:93], v[244:245]
	v_pk_add_f32 v[92:93], v[92:93], v[246:247]
	v_pk_add_f32 v[92:93], v[92:93], v[248:249]
	v_pk_add_f32 v[92:93], v[92:93], v[250:251]
	s_nop 0
	v_add_f32_e32 v92, v92, v93
	v_mov_b32_e32 v215, v92
	v_cvt_pk_f16_f32 v232, v236, v237
	v_cvt_pk_f16_f32 v233, v238, v239
	v_cvt_pk_f16_f32 v234, v240, v241
	v_cvt_pk_f16_f32 v235, v242, v243
	v_cvt_pk_f16_f32 v228, v244, v245
	v_cvt_pk_f16_f32 v229, v246, v247
	v_cvt_pk_f16_f32 v230, v248, v249
	v_cvt_pk_f16_f32 v231, v250, v251
	v_permlane32_swap_b32 v215, v92
	v_add_f32_e32 v92, v92, v215
	v_fma_f32 v198, v198, v88, v92
	ds_read_b128 v[236:239], v199 offset:34912
	ds_read_b128 v[240:243], v199 offset:39488
	ds_read_b128 v[244:247], v199 offset:44064
	ds_read_b128 v[248:251], v199 offset:48640
	s_cbranch_vccz .LdsaA_s1_noresc
	v_pk_mul_f32 v[64:65], v[64:65], v[88:89] op_sel_hi:[1,0]
	v_pk_mul_f32 v[66:67], v[66:67], v[88:89] op_sel_hi:[1,0]
	v_pk_mul_f32 v[68:69], v[68:69], v[88:89] op_sel_hi:[1,0]
	v_pk_mul_f32 v[70:71], v[70:71], v[88:89] op_sel_hi:[1,0]
	v_pk_mul_f32 v[72:73], v[72:73], v[88:89] op_sel_hi:[1,0]
	v_pk_mul_f32 v[74:75], v[74:75], v[88:89] op_sel_hi:[1,0]
	v_pk_mul_f32 v[76:77], v[76:77], v[88:89] op_sel_hi:[1,0]
	v_pk_mul_f32 v[78:79], v[78:79], v[88:89] op_sel_hi:[1,0]
	v_pk_mul_f32 v[48:49], v[48:49], v[88:89] op_sel_hi:[1,0]
	v_pk_mul_f32 v[50:51], v[50:51], v[88:89] op_sel_hi:[1,0]
	v_pk_mul_f32 v[52:53], v[52:53], v[88:89] op_sel_hi:[1,0]
	v_pk_mul_f32 v[54:55], v[54:55], v[88:89] op_sel_hi:[1,0]
	v_pk_mul_f32 v[56:57], v[56:57], v[88:89] op_sel_hi:[1,0]
	v_pk_mul_f32 v[58:59], v[58:59], v[88:89] op_sel_hi:[1,0]
	v_pk_mul_f32 v[60:61], v[60:61], v[88:89] op_sel_hi:[1,0]
	v_pk_mul_f32 v[62:63], v[62:63], v[88:89] op_sel_hi:[1,0]
	v_pk_mul_f32 v[32:33], v[32:33], v[88:89] op_sel_hi:[1,0]
	v_pk_mul_f32 v[34:35], v[34:35], v[88:89] op_sel_hi:[1,0]
	v_pk_mul_f32 v[36:37], v[36:37], v[88:89] op_sel_hi:[1,0]
	v_pk_mul_f32 v[38:39], v[38:39], v[88:89] op_sel_hi:[1,0]
	v_pk_mul_f32 v[40:41], v[40:41], v[88:89] op_sel_hi:[1,0]
	v_pk_mul_f32 v[42:43], v[42:43], v[88:89] op_sel_hi:[1,0]
	v_pk_mul_f32 v[44:45], v[44:45], v[88:89] op_sel_hi:[1,0]
	v_pk_mul_f32 v[46:47], v[46:47], v[88:89] op_sel_hi:[1,0]
	v_pk_mul_f32 v[16:17], v[16:17], v[88:89] op_sel_hi:[1,0]
	v_pk_mul_f32 v[18:19], v[18:19], v[88:89] op_sel_hi:[1,0]
	v_pk_mul_f32 v[20:21], v[20:21], v[88:89] op_sel_hi:[1,0]
	v_pk_mul_f32 v[22:23], v[22:23], v[88:89] op_sel_hi:[1,0]
	v_pk_mul_f32 v[24:25], v[24:25], v[88:89] op_sel_hi:[1,0]
	v_pk_mul_f32 v[26:27], v[26:27], v[88:89] op_sel_hi:[1,0]
	v_pk_mul_f32 v[28:29], v[28:29], v[88:89] op_sel_hi:[1,0]
	v_pk_mul_f32 v[30:31], v[30:31], v[88:89] op_sel_hi:[1,0]

; #define LAS __attribute__((address_space(3)))
; __device__ __forceinline__ void diff_attn_item(CParams& p, int j, int layer, LAS unsigned char* lds, int b, int h, int qb, int tid_in, int lane_in, int wave) {
;     ...
;         mx = fmaxf(mx, __shfl_xor(mx, 32));
;         const float m_new = fmaxf(m_run, mx);
;         const float alpha = __builtin_amdgcn_exp2f(m_run - m_new);
;         const bool resc = __ballot(m_new > m_run) != 0ull;
;         float ls = 0.f;
; #pragma unroll
;         for (int sub = 0; sub < 2; ++sub)
; #pragma unroll
;             for (int i = 0; i < 16; ++i) { const float e = __builtin_amdgcn_exp2f(sc[sub][i] - m_new); sc[sub][i] = e; ls += e; }
;         ls += __shfl_xor(ls, 32);
;         l_run = l_run * alpha + ls; m_run = m_new;
;         if (resc) {
; #pragma unroll
;             for (int d = 0; d < 4; ++d)
; #pragma unroll
;                 for (int i = 0; i < 16; ++i) o[d][i] *= alpha;
;         }
;     ...
; #pragma unroll
;                 for (int d = 0; d < 4; ++d) {
;                     const int coff = 32 * d * 72 + ((((sub << 1) | s2) ^ d) << 4);
;                     const h16x4 lo = *(const LAS h16x4*)(Vt + vlo + coff), hi = *(const LAS h16x4*)(Vt + vhi + coff);
.LdiffA_max:
	v_max3_f32 v249, v162, v163, v164
	v_max3_f32 v249, v249, v165, v166
	v_max3_f32 v249, v249, v167, v168
	v_max3_f32 v249, v249, v169, v170
	v_max3_f32 v249, v249, v171, v172
	v_max3_f32 v249, v249, v173, v174
	v_max3_f32 v249, v249, v175, v176
	v_max3_f32 v249, v249, v177, v228
	v_max3_f32 v249, v249, v229, v230
	v_max3_f32 v249, v249, v231, v232
	v_max3_f32 v249, v249, v233, v234
	v_max3_f32 v249, v249, v235, v236
	v_max3_f32 v249, v249, v237, v238
	v_max3_f32 v249, v249, v239, v240
	v_max3_f32 v249, v249, v241, v242
	v_max_f32_e32 v249, v249, v243
	s_waitcnt lgkmcnt(0)
	v_add_f32_e32 v249, v249, v213
	v_mov_b32_e32 v251, v249
	ds_read_b128 v[66:69], v215 offset:34816
	ds_read_b128 v[70:73], v215 offset:39456
	ds_read_b128 v[74:77], v215 offset:44096
	ds_read_b128 v[78:81], v215 offset:48736
	ds_read_b128 v[82:85], v215 offset:34848
	ds_read_b128 v[86:89], v215 offset:39424
	ds_read_b128 v[90:93], v215 offset:44128
	ds_read_b128 v[94:97], v215 offset:48704
	v_permlane32_swap_b32 v251, v249
	v_max3_f32 v248, v201, v249, v251
	v_sub_f32_e32 v244, v201, v248
	v_exp_f32_e32 v244, v244
	v_cmp_gt_f32_e32 vcc, v248, v201
	v_sub_f32_e32 v246, v248, v213
	v_mov_b32_e32 v201, v248
	v_pk_add_f32 v[162:163], v[162:163], v[246:247] op_sel_hi:[1,0] neg_lo:[0,1] neg_hi:[0,1]
	v_pk_add_f32 v[164:165], v[164:165], v[246:247] op_sel_hi:[1,0] neg_lo:[0,1] neg_hi:[0,1]
	v_pk_add_f32 v[166:167], v[166:167], v[246:247] op_sel_hi:[1,0] neg_lo:[0,1] neg_hi:[0,1]
	v_pk_add_f32 v[168:169], v[168:169], v[246:247] op_sel_hi:[1,0] neg_lo:[0,1] neg_hi:[0,1]
	v_pk_add_f32 v[170:171], v[170:171], v[246:247] op_sel_hi:[1,0] neg_lo:[0,1] neg_hi:[0,1]
	v_pk_add_f32 v[172:173], v[172:173], v[246:247] op_sel_hi:[1,0] neg_lo:[0,1] neg_hi:[0,1]
	v_pk_add_f32 v[174:175], v[174:175], v[246:247] op_sel_hi:[1,0] neg_lo:[0,1] neg_hi:[0,1]
	v_pk_add_f32 v[176:177], v[176:177], v[246:247] op_sel_hi:[1,0] neg_lo:[0,1] neg_hi:[0,1]
	v_pk_add_f32 v[228:229], v[228:229], v[246:247] op_sel_hi:[1,0] neg_lo:[0,1] neg_hi:[0,1]
	v_pk_add_f32 v[230:231], v[230:231], v[246:247] op_sel_hi:[1,0] neg_lo:[0,1] neg_hi:[0,1]
	v_pk_add_f32 v[232:233], v[232:233], v[246:247] op_sel_hi:[1,0] neg_lo:[0,1] neg_hi:[0,1]
	v_pk_add_f32 v[234:235], v[234:235], v[246:247] op_sel_hi:[1,0] neg_lo:[0,1] neg_hi:[0,1]
	v_pk_add_f32 v[236:237], v[236:237], v[246:247] op_sel_hi:[1,0] neg_lo:[0,1] neg_hi:[0,1]
	v_pk_add_f32 v[238:239], v[238:239], v[246:247] op_sel_hi:[1,0] neg_lo:[0,1] neg_hi:[0,1]
	v_pk_add_f32 v[240:241], v[240:241], v[246:247] op_sel_hi:[1,0] neg_lo:[0,1] neg_hi:[0,1]
	v_pk_add_f32 v[242:243], v[242:243], v[246:247] op_sel_hi:[1,0] neg_lo:[0,1] neg_hi:[0,1]
	v_exp_f32_e32 v162, v162
	v_exp_f32_e32 v163, v163
	v_exp_f32_e32 v164, v164
	v_exp_f32_e32 v165, v165
	v_exp_f32_e32 v166, v166
	v_exp_f32_e32 v167, v167
	v_exp_f32_e32 v168, v168
	v_exp_f32_e32 v169, v169
	v_exp_f32_e32 v170, v170
	v_exp_f32_e32 v171, v171
	v_exp_f32_e32 v172, v172
	v_exp_f32_e32 v173, v173
	v_exp_f32_e32 v174, v174
	v_exp_f32_e32 v175, v175
	v_exp_f32_e32 v176, v176
	v_exp_f32_e32 v177, v177
	v_exp_f32_e32 v228, v228
	v_exp_f32_e32 v229, v229
	v_exp_f32_e32 v230, v230
	v_exp_f32_e32 v231, v231
	v_exp_f32_e32 v232, v232
	v_exp_f32_e32 v233, v233
	v_exp_f32_e32 v234, v234
	v_exp_f32_e32 v235, v235
	v_exp_f32_e32 v236, v236
	v_exp_f32_e32 v237, v237
	v_exp_f32_e32 v238, v238
	v_exp_f32_e32 v239, v239
	v_exp_f32_e32 v240, v240
	v_exp_f32_e32 v241, v241
	v_exp_f32_e32 v242, v242
	v_exp_f32_e32 v243, v243
	v_pk_add_f32 v[250:251], v[162:163], v[164:165]
	v_pk_add_f32 v[250:251], v[250:251], v[166:167]
	v_pk_add_f32 v[250:251], v[250:251], v[168:169]
	v_pk_add_f32 v[250:251], v[250:251], v[170:171]
	v_pk_add_f32 v[250:251], v[250:251], v[172:173]
	v_pk_add_f32 v[250:251], v[250:251], v[174:175]
	v_pk_add_f32 v[250:251], v[250:251], v[176:177]
	v_pk_add_f32 v[250:251], v[250:251], v[228:229]
	v_pk_add_f32 v[250:251], v[250:251], v[230:231]
	v_pk_add_f32 v[250:251], v[250:251], v[232:233]
	v_pk_add_f32 v[250:251], v[250:251], v[234:235]
	v_pk_add_f32 v[250:251], v[250:251], v[236:237]
	v_pk_add_f32 v[250:251], v[250:251], v[238:239]
	v_pk_add_f32 v[250:251], v[250:251], v[240:241]
	v_pk_add_f32 v[250:251], v[250:251], v[242:243]
	s_nop 0
	v_add_f32_e32 v250, v250, v251
	v_mov_b32_e32 v251, v250
	v_cvt_pk_f16_f32 v144, v162, v163
	v_cvt_pk_f16_f32 v145, v164, v165
	v_cvt_pk_f16_f32 v146, v166, v167
	v_cvt_pk_f16_f32 v147, v168, v169
	v_cvt_pk_f16_f32 v148, v170, v171
	v_cvt_pk_f16_f32 v149, v172, v173
	v_cvt_pk_f16_f32 v150, v174, v175
	v_cvt_pk_f16_f32 v151, v176, v177
	v_cvt_pk_f16_f32 v152, v228, v229
	v_cvt_pk_f16_f32 v153, v230, v231
	v_cvt_pk_f16_f32 v154, v232, v233
	v_cvt_pk_f16_f32 v155, v234, v235
	v_cvt_pk_f16_f32 v178, v236, v237
	v_cvt_pk_f16_f32 v179, v238, v239
	v_cvt_pk_f16_f32 v180, v240, v241
	v_cvt_pk_f16_f32 v181, v242, v243
	v_permlane32_swap_b32 v251, v250
	v_add_f32_e32 v250, v250, v251
	v_fma_f32 v197, v197, v244, v250
	s_cbranch_vccz .LdiffA_noresc
	v_pk_mul_f32 v[50:51], v[50:51], v[244:245] op_sel_hi:[1,0]
	v_pk_mul_f32 v[52:53], v[52:53], v[244:245] op_sel_hi:[1,0]
	v_pk_mul_f32 v[54:55], v[54:55], v[244:245] op_sel_hi:[1,0]
	v_pk_mul_f32 v[56:57], v[56:57], v[244:245] op_sel_hi:[1,0]
	v_pk_mul_f32 v[58:59], v[58:59], v[244:245] op_sel_hi:[1,0]
	v_pk_mul_f32 v[60:61], v[60:61], v[244:245] op_sel_hi:[1,0]
	v_pk_mul_f32 v[62:63], v[62:63], v[244:245] op_sel_hi:[1,0]
	v_pk_mul_f32 v[64:65], v[64:65], v[244:245] op_sel_hi:[1,0]
	v_pk_mul_f32 v[34:35], v[34:35], v[244:245] op_sel_hi:[1,0]
	v_pk_mul_f32 v[36:37], v[36:37], v[244:245] op_sel_hi:[1,0]
	v_pk_mul_f32 v[38:39], v[38:39], v[244:245] op_sel_hi:[1,0]
	v_pk_mul_f32 v[40:41], v[40:41], v[244:245] op_sel_hi:[1,0]
	v_pk_mul_f32 v[42:43], v[42:43], v[244:245] op_sel_hi:[1,0]
	v_pk_mul_f32 v[44:45], v[44:45], v[244:245] op_sel_hi:[1,0]
	v_pk_mul_f32 v[46:47], v[46:47], v[244:245] op_sel_hi:[1,0]
	v_pk_mul_f32 v[48:49], v[48:49], v[244:245] op_sel_hi:[1,0]
	v_pk_mul_f32 v[18:19], v[18:19], v[244:245] op_sel_hi:[1,0]
	v_pk_mul_f32 v[20:21], v[20:21], v[244:245] op_sel_hi:[1,0]
	v_pk_mul_f32 v[22:23], v[22:23], v[244:245] op_sel_hi:[1,0]
	v_pk_mul_f32 v[24:25], v[24:25], v[244:245] op_sel_hi:[1,0]
	v_pk_mul_f32 v[26:27], v[26:27], v[244:245] op_sel_hi:[1,0]
	v_pk_mul_f32 v[28:29], v[28:29], v[244:245] op_sel_hi:[1,0]
	v_pk_mul_f32 v[30:31], v[30:31], v[244:245] op_sel_hi:[1,0]
	v_pk_mul_f32 v[32:33], v[32:33], v[244:245] op_sel_hi:[1,0]
	v_pk_mul_f32 v[2:3], v[2:3], v[244:245] op_sel_hi:[1,0]
	v_pk_mul_f32 v[4:5], v[4:5], v[244:245] op_sel_hi:[1,0]
	v_pk_mul_f32 v[6:7], v[6:7], v[244:245] op_sel_hi:[1,0]
	v_pk_mul_f32 v[8:9], v[8:9], v[244:245] op_sel_hi:[1,0]
	v_pk_mul_f32 v[10:11], v[10:11], v[244:245] op_sel_hi:[1,0]
	v_pk_mul_f32 v[12:13], v[12:13], v[244:245] op_sel_hi:[1,0]
	v_pk_mul_f32 v[14:15], v[14:15], v[244:245] op_sel_hi:[1,0]
	v_pk_mul_f32 v[16:17], v[16:17], v[244:245] op_sel_hi:[1,0]
; #define LAS __attribute__((address_space(3)))
; __device__ __forceinline__ f32x16 mma32(const h16x8 a, const h16x8 b, const f32x16 c) { return __builtin_amdgcn_mfma_f32_32x32x16_f16(a, b, c, 0, 0, 0); }
; __device__ __forceinline__ void diff_attn_item(CParams& p, int j, int layer, LAS unsigned char* lds, int b, int h, int qb, int tid_in, int lane_in, int wave) {
;     ...
; #pragma unroll
;         for (int sub = 0; sub < 2; ++sub)
; #pragma unroll
;             for (int s2 = 0; s2 < 2; ++s2) {
;                 h16x8 pf;
; #pragma unroll
;                 for (int jj = 0; jj < 8; ++jj) pf[jj] = (h16)sc[sub][8 * s2 + jj];
; #pragma unroll
;                 for (int d = 0; d < 4; ++d) {
;                     const int coff = 32 * d * 72 + ((((sub << 1) | s2) ^ d) << 4);
;                     const h16x4 lo = *(const LAS h16x4*)(Vt + vlo + coff), hi = *(const LAS h16x4*)(Vt + vhi + coff);
;                     h16x8 vf; vf[0] = lo[0]; vf[1] = lo[1]; vf[2] = lo[2]; vf[3] = lo[3]; vf[4] = hi[0]; vf[5] = hi[1]; vf[6] = hi[2]; vf[7] = hi[3];
;                     o[d] = mma32(vf, pf, o[d]);
;                 }
;             }
.LdiffA_noresc:
	s_waitcnt lgkmcnt(4)
	v_mfma_f32_32x32x16_f16 v[50:65], v[66:69], v[144:147], v[50:65]
	v_mfma_f32_32x32x16_f16 v[34:49], v[70:73], v[144:147], v[34:49]
	v_mfma_f32_32x32x16_f16 v[18:33], v[74:77], v[144:147], v[18:33]
	v_mfma_f32_32x32x16_f16 v[2:17], v[78:81], v[144:147], v[2:17]
	ds_read_b128 v[66:69], v215 offset:34880
	ds_read_b128 v[70:73], v215 offset:39520
	ds_read_b128 v[74:77], v215 offset:44032
	ds_read_b128 v[78:81], v215 offset:48672
	s_waitcnt lgkmcnt(4)
	v_mfma_f32_32x32x16_f16 v[50:65], v[82:85], v[148:151], v[50:65]
	v_mfma_f32_32x32x16_f16 v[34:49], v[86:89], v[148:151], v[34:49]
	v_mfma_f32_32x32x16_f16 v[18:33], v[90:93], v[148:151], v[18:33]
	v_mfma_f32_32x32x16_f16 v[2:17], v[94:97], v[148:151], v[2:17]
	ds_read_b128 v[82:85], v215 offset:34912
	ds_read_b128 v[86:89], v215 offset:39488
	ds_read_b128 v[90:93], v215 offset:44064
	ds_read_b128 v[94:97], v215 offset:48640
	s_waitcnt lgkmcnt(4)
	v_mfma_f32_32x32x16_f16 v[50:65], v[66:69], v[152:155], v[50:65]
	v_mfma_f32_32x32x16_f16 v[34:49], v[70:73], v[152:155], v[34:49]
	v_mfma_f32_32x32x16_f16 v[18:33], v[74:77], v[152:155], v[18:33]
	v_mfma_f32_32x32x16_f16 v[2:17], v[78:81], v[152:155], v[2:17]
	s_waitcnt lgkmcnt(0)
	v_mfma_f32_32x32x16_f16 v[50:65], v[82:85], v[178:181], v[50:65]
	v_mfma_f32_32x32x16_f16 v[34:49], v[86:89], v[178:181], v[34:49]
	v_mfma_f32_32x32x16_f16 v[18:33], v[90:93], v[178:181], v[18:33]
	v_mfma_f32_32x32x16_f16 v[2:17], v[94:97], v[178:181], v[2:17]
